# v13 + attn_prompt_unit pre-barrier load chain de-serialised: V loads and T5B bucket byte issued with the K loads, REL bias load right after the K block
# speedup vs baseline: 1.0117x; 1.0117x over previous
.LBB0_182:
	s_or_b64 exec, exec, s[0:1]
	v_and_b32_e32 v174, 0x7f, v88
	s_getpc_b64 s[14:15]
	s_add_u32 s14, s14, _ZL3T5B@rel32@lo+4
	s_addc_u32 s15, s15, _ZL3T5B@rel32@hi+12
	global_load_ubyte v174, v174, s[14:15]
	s_ashr_i32 s16, s97, 2
	s_ashr_i32 s17, s16, 31
	s_lshl_b64 s[16:17], s[16:17], 7
	s_add_u32 s16, s16, 0xffffff80
	s_addc_u32 s17, s17, -1
	v_and_b32_e32 v196, 0xff, v88
	v_mov_b32_e32 v197, 0
	v_lshl_add_u64 v[196:197], s[16:17], 0, v[196:197]
	v_readlane_b32 s16, v254, 32
	v_readlane_b32 s17, v254, 33
	s_and_b32 s18, s97, 3
	s_lshl_b32 s18, s18, 7
	s_mov_b32 s19, 0
	v_ashrrev_i32_e32 v198, 8, v88
	v_lshlrev_b32_e32 v198, 6, v198
	v_mov_b32_e32 v199, 0
	v_mov_b64_e32 v[176:177], s[16:17]
	s_nop 0
	v_mad_u64_u32 v[176:177], s[20:21], v196, s95, v[176:177]
	v_mad_i32_i24 v177, v197, s95, v177
	v_lshl_add_u64 v[176:177], v[176:177], 0, s[18:19]
	v_lshl_add_u64 v[176:177], v[176:177], 0, v[198:199]
	s_mov_b64 s[18:19], 0x1200
	v_lshl_add_u64 v[176:177], v[176:177], 0, s[18:19]
	global_load_dwordx4 v[180:183], v[176:177], off
	global_load_dwordx4 v[184:187], v[176:177], off offset:16
	global_load_dwordx4 v[188:191], v[176:177], off offset:32
	global_load_dwordx4 v[192:195], v[176:177], off offset:48
	s_ashr_i32 s0, s97, 2
	s_and_b32 s6, s0, 31
	v_ashrrev_i32_e32 v34, 1, v88
	s_cmp_lg_u32 s6, 0
	s_movk_i32 s1, 0x7f
	s_waitcnt vmcnt(20)
	v_and_b32_e32 v3, 1, v89
	s_cselect_b64 s[4:5], -1, 0
	v_cmp_lt_i32_e32 vcc, s1, v34
	s_nor_b64 s[2:3], s[4:5], vcc
	v_lshlrev_b32_e32 v0, 5, v3
	s_and_saveexec_b64 s[8:9], s[2:3]
	s_xor_b64 s[2:3], exec, s[8:9]
	s_or_saveexec_b64 s[2:3], s[2:3]
	s_ashr_i32 s1, s0, 31
	s_and_b32 s10, s97, 3
	s_lshl_b64 s[78:79], s[0:1], 7
	v_mov_b32_e32 v2, 0
	v_lshlrev_b32_e32 v36, 6, v3
	v_mov_b32_e32 v3, 0
	v_mov_b32_e32 v4, 0
	v_mov_b32_e32 v5, 0
	s_waitcnt vmcnt(19)
	v_mov_b32_e32 v6, 0
	v_mov_b32_e32 v7, 0
	v_mov_b32_e32 v8, 0
	v_mov_b32_e32 v9, 0
	s_waitcnt vmcnt(16)
	v_mov_b32_e32 v18, 0
	v_mov_b32_e32 v19, 0
	v_mov_b32_e32 v20, 0
	v_mov_b32_e32 v21, 0
	s_waitcnt vmcnt(15)
	v_mov_b32_e32 v22, 0
	v_mov_b32_e32 v23, 0
	v_mov_b32_e32 v24, 0
	v_mov_b32_e32 v25, 0
	v_mov_b32_e32 v38, 0
	v_mov_b32_e32 v39, 0
	v_mov_b32_e32 v40, 0
	v_mov_b32_e32 v41, 0
	v_mov_b32_e32 v42, 0
	v_mov_b32_e32 v43, 0
	v_mov_b32_e32 v44, 0
	v_mov_b32_e32 v45, 0
	v_mov_b32_e32 v46, 0
	v_mov_b32_e32 v47, 0
	v_mov_b32_e32 v48, 0
	v_mov_b32_e32 v49, 0
	v_mov_b32_e32 v50, 0
	v_mov_b32_e32 v51, 0
	v_mov_b32_e32 v52, 0
	v_mov_b32_e32 v53, 0
	s_xor_b64 exec, exec, s[2:3]
	s_cbranch_execz .LBB0_184
	s_add_u32 s0, s78, 0xffffff80
	s_addc_u32 s1, s79, -1
	v_ashrrev_i32_e32 v35, 31, v34
	v_lshl_add_u64 v[2:3], s[0:1], 0, v[34:35]
	v_readlane_b32 s0, v254, 32
	v_readlane_b32 s1, v254, 33
	s_lshl_b32 s92, s10, 7
	v_mov_b32_e32 v37, v1
	v_mov_b64_e32 v[4:5], s[0:1]
	v_mad_u64_u32 v[4:5], s[0:1], v2, s95, v[4:5]
	v_mad_i32_i24 v5, v3, s95, v5
	v_lshl_add_u64 v[2:3], v[4:5], 0, s[92:93]
	v_lshl_add_u64 v[2:3], v[2:3], 0, v[36:37]
	s_movk_i32 s0, 0x1000
	v_add_co_u32_e64 v4, s[0:1], s0, v2
	s_nop 1
	v_addc_co_u32_e64 v5, s[0:1], 0, v3, s[0:1]
	s_mov_b64 s[0:1], 0x1000
	s_nop 0
	v_lshl_add_u64 v[2:3], v[2:3], 0, s[0:1]
	global_load_dwordx4 v[6:9], v[4:5], off
	global_load_dwordx4 v[10:13], v[2:3], off offset:16
	global_load_dwordx4 v[14:17], v[2:3], off offset:32
	global_load_dwordx4 v[26:29], v[2:3], off offset:48
	s_waitcnt vmcnt(2)
	v_lshlrev_b32_e32 v18, 16, v10
	v_lshlrev_b32_e32 v2, 16, v6
	v_and_b32_e32 v3, 0xffff0000, v6
	v_lshlrev_b32_e32 v4, 16, v7
	v_and_b32_e32 v5, 0xffff0000, v7
	v_lshlrev_b32_e32 v6, 16, v8
	v_and_b32_e32 v7, 0xffff0000, v8
	v_lshlrev_b32_e32 v8, 16, v9
	v_and_b32_e32 v9, 0xffff0000, v9
	v_and_b32_e32 v19, 0xffff0000, v10
	v_lshlrev_b32_e32 v20, 16, v11
	v_and_b32_e32 v21, 0xffff0000, v11
	v_lshlrev_b32_e32 v22, 16, v12
	v_and_b32_e32 v23, 0xffff0000, v12
	v_lshlrev_b32_e32 v24, 16, v13
	v_and_b32_e32 v25, 0xffff0000, v13
	s_waitcnt vmcnt(1)
	v_lshlrev_b32_e32 v38, 16, v14
	v_and_b32_e32 v39, 0xffff0000, v14
	v_lshlrev_b32_e32 v40, 16, v15
	v_and_b32_e32 v41, 0xffff0000, v15
	v_lshlrev_b32_e32 v42, 16, v16
	v_and_b32_e32 v43, 0xffff0000, v16
	v_lshlrev_b32_e32 v44, 16, v17
	v_and_b32_e32 v45, 0xffff0000, v17
	s_waitcnt vmcnt(0)
	v_lshlrev_b32_e32 v46, 16, v26
	v_and_b32_e32 v47, 0xffff0000, v26
	v_lshlrev_b32_e32 v48, 16, v27
	v_and_b32_e32 v49, 0xffff0000, v27
	v_lshlrev_b32_e32 v50, 16, v28
	v_and_b32_e32 v51, 0xffff0000, v28
	v_lshlrev_b32_e32 v52, 16, v29
	v_and_b32_e32 v53, 0xffff0000, v29
.LBB0_184:
	s_or_b64 exec, exec, s[2:3]
	s_waitcnt vmcnt(0)
	v_readlane_b32 s14, v253, 21
	v_ashrrev_i32_e32 v176, 7, v88
	s_lshl_b32 s15, s10, 2
	v_lshlrev_b32_e32 v174, 4, v174
	v_mov_b32_e32 v178, s14
	ds_read_b64 v[178:179], v178
	v_add3_u32 v176, v176, s15, v174
	v_ashrrev_i32_e32 v177, 31, v176
	s_waitcnt lgkmcnt(0)
	v_lshl_add_u64 v[178:179], v[176:177], 2, v[178:179]
	global_load_dword v175, v[178:179], off
	v_pk_mul_f32 v[10:11], v[2:3], v[2:3]
	v_pk_mul_f32 v[12:13], v[4:5], v[4:5]
	v_add_f32_e32 v10, v11, v10
	v_add_f32_e32 v10, v12, v10
	v_pk_mul_f32 v[14:15], v[6:7], v[6:7]
	v_add_f32_e32 v10, v13, v10
	v_add_f32_e32 v10, v14, v10
	v_pk_mul_f32 v[16:17], v[8:9], v[8:9]
	v_add_f32_e32 v10, v15, v10
	v_add_f32_e32 v10, v16, v10
	s_waitcnt vmcnt(9)
	v_pk_mul_f32 v[26:27], v[18:19], v[18:19]
	v_add_f32_e32 v10, v17, v10
	v_add_f32_e32 v10, v26, v10
	v_pk_mul_f32 v[28:29], v[20:21], v[20:21]
	v_add_f32_e32 v10, v27, v10
	v_add_f32_e32 v10, v28, v10
	s_waitcnt vmcnt(8)
	v_pk_mul_f32 v[30:31], v[22:23], v[22:23]
	v_add_f32_e32 v10, v29, v10
	v_add_f32_e32 v10, v30, v10
	v_pk_mul_f32 v[32:33], v[24:25], v[24:25]
	v_add_f32_e32 v10, v31, v10
	v_add_f32_e32 v10, v32, v10
	v_pk_mul_f32 v[54:55], v[38:39], v[38:39]
	v_add_f32_e32 v10, v33, v10
	v_add_f32_e32 v10, v54, v10
	v_pk_mul_f32 v[56:57], v[40:41], v[40:41]
	v_add_f32_e32 v10, v55, v10
	v_add_f32_e32 v10, v56, v10
	v_pk_mul_f32 v[58:59], v[42:43], v[42:43]
	v_add_f32_e32 v10, v57, v10
	v_add_f32_e32 v10, v58, v10
	v_pk_mul_f32 v[60:61], v[44:45], v[44:45]
	v_add_f32_e32 v10, v59, v10
	v_add_f32_e32 v10, v60, v10
	v_pk_mul_f32 v[62:63], v[46:47], v[46:47]
	v_add_f32_e32 v10, v61, v10
	v_add_f32_e32 v10, v62, v10
	v_pk_mul_f32 v[64:65], v[48:49], v[48:49]
	v_add_f32_e32 v10, v63, v10
	v_add_f32_e32 v10, v64, v10
	v_pk_mul_f32 v[66:67], v[50:51], v[50:51]
	v_add_f32_e32 v10, v65, v10
	v_and_b32_e32 v12, 64, v211
	v_add_f32_e32 v10, v66, v10
	v_xor_b32_e32 v11, 1, v211
	v_add_u32_e32 v76, 64, v12
	v_pk_mul_f32 v[70:71], v[52:53], v[52:53]
	v_add_f32_e32 v10, v67, v10
	v_cmp_lt_i32_e64 s[0:1], v11, v76
	v_add_f32_e32 v10, v70, v10
	v_add_f32_e32 v10, v71, v10
	v_cndmask_b32_e64 v11, v211, v11, s[0:1]
	v_lshlrev_b32_e32 v11, 2, v11
	ds_bpermute_b32 v11, v11, v10
	s_ashr_i32 s2, s97, 7
	s_cmp_eq_u32 s6, 31
	s_cselect_b64 s[6:7], -1, 0
	s_and_b64 s[8:9], s[6:7], vcc
	s_waitcnt lgkmcnt(0)
	v_add_f32_e32 v10, v10, v11
	v_fmamk_f32 v10, v10, 0x3c800000, v240
	v_cmp_gt_f32_e64 s[0:1], s72, v10
	v_mul_f32_e32 v11, 0x4b800000, v10
	s_nop 0
	v_cndmask_b32_e64 v10, v10, v11, s[0:1]
	v_rsq_f32_e32 v10, v10
	s_nop 0
	v_mul_f32_e32 v11, 0x45800000, v10
	v_cndmask_b32_e64 v54, v10, v11, s[0:1]
	v_readlane_b32 s0, v253, 20
	s_nop 1
	v_mov_b32_e32 v10, s0
	ds_read_b64 v[10:11], v10
	s_movk_i32 s0, 0x90
	v_mul_lo_u32 v35, v34, s0
	v_add3_u32 v35, 0, v35, v36
	s_waitcnt lgkmcnt(0)
	v_lshl_add_u64 v[56:57], v[0:1], 2, v[10:11]
	global_load_dwordx4 v[26:29], v[56:57], off offset:48
	global_load_dwordx4 v[30:33], v[56:57], off offset:32
	global_load_dwordx4 v[10:13], v[56:57], off offset:16
	global_load_dwordx4 v[14:17], v[56:57], off
	s_waitcnt vmcnt(0)
	v_pk_mul_f32 v[14:15], v[14:15], v[54:55] op_sel_hi:[1,0]
	s_nop 0
	v_pk_mul_f32 v[14:15], v[2:3], v[14:15]
	v_pk_mul_f32 v[2:3], v[16:17], v[54:55] op_sel_hi:[1,0]
	v_cvt_pk_bf16_f32 v36, v14, v15
	v_pk_mul_f32 v[16:17], v[4:5], v[2:3]
	v_pk_mul_f32 v[2:3], v[10:11], v[54:55] op_sel_hi:[1,0]
	v_pk_mul_f32 v[4:5], v[28:29], v[54:55] op_sel_hi:[1,0]
	v_pk_mul_f32 v[10:11], v[6:7], v[2:3]
	v_pk_mul_f32 v[2:3], v[12:13], v[54:55] op_sel_hi:[1,0]
	v_pk_mul_f32 v[4:5], v[24:25], v[4:5]
	v_pk_mul_f32 v[12:13], v[8:9], v[2:3]
	v_pk_mul_f32 v[2:3], v[30:31], v[54:55] op_sel_hi:[1,0]
	v_cvt_pk_bf16_f32 v37, v16, v17
	v_pk_mul_f32 v[6:7], v[18:19], v[2:3]
	v_pk_mul_f32 v[2:3], v[32:33], v[54:55] op_sel_hi:[1,0]
	s_nop 0
	v_pk_mul_f32 v[8:9], v[20:21], v[2:3]
	v_pk_mul_f32 v[2:3], v[26:27], v[54:55] op_sel_hi:[1,0]
	s_nop 0
	v_pk_mul_f32 v[2:3], v[22:23], v[2:3]
	global_load_dwordx4 v[18:21], v[56:57], off offset:112
	global_load_dwordx4 v[22:25], v[56:57], off offset:96
	global_load_dwordx4 v[26:29], v[56:57], off offset:80
	global_load_dwordx4 v[30:33], v[56:57], off offset:64
	s_waitcnt vmcnt(3)
	v_pk_mul_f32 v[18:19], v[54:55], v[18:19] op_sel_hi:[0,1]
	s_waitcnt vmcnt(2)
	v_pk_mul_f32 v[22:23], v[22:23], v[54:55] op_sel_hi:[1,0]
	s_waitcnt vmcnt(1)
	v_pk_mul_f32 v[26:27], v[26:27], v[54:55] op_sel_hi:[1,0]
	s_waitcnt vmcnt(0)
	v_pk_mul_f32 v[30:31], v[30:31], v[54:55] op_sel_hi:[1,0]
	v_pk_mul_f32 v[32:33], v[32:33], v[54:55] op_sel_hi:[1,0]
	v_pk_mul_f32 v[30:31], v[38:39], v[30:31]
	v_pk_mul_f32 v[28:29], v[28:29], v[54:55] op_sel_hi:[1,0]
	v_cvt_pk_bf16_f32 v38, v10, v11
	v_cvt_pk_bf16_f32 v39, v12, v13
	v_pk_mul_f32 v[32:33], v[40:41], v[32:33]
	v_pk_mul_f32 v[26:27], v[42:43], v[26:27]
	v_pk_mul_f32 v[28:29], v[44:45], v[28:29]
	v_pk_mul_f32 v[24:25], v[24:25], v[54:55] op_sel_hi:[1,0]
	v_pk_mul_f32 v[20:21], v[54:55], v[20:21] op_sel_hi:[0,1]
	ds_write_b128 v35, v[36:39]
	v_cvt_pk_bf16_f32 v36, v6, v7
	v_cvt_pk_bf16_f32 v37, v8, v9
	v_cvt_pk_bf16_f32 v38, v2, v3
	v_cvt_pk_bf16_f32 v39, v4, v5
	v_pk_mul_f32 v[22:23], v[46:47], v[22:23]
	v_pk_mul_f32 v[24:25], v[48:49], v[24:25]
	v_pk_mul_f32 v[18:19], v[50:51], v[18:19]
	v_pk_mul_f32 v[20:21], v[52:53], v[20:21]
	ds_write_b128 v35, v[36:39] offset:16
	v_cvt_pk_bf16_f32 v36, v30, v31
	v_cvt_pk_bf16_f32 v37, v32, v33
	v_cvt_pk_bf16_f32 v38, v26, v27
	v_cvt_pk_bf16_f32 v39, v28, v29
	ds_write_b128 v35, v[36:39] offset:32
	v_cvt_pk_bf16_f32 v36, v22, v23
	v_cvt_pk_bf16_f32 v37, v24, v25
	v_cvt_pk_bf16_f32 v38, v18, v19
	v_cvt_pk_bf16_f32 v39, v20, v21
	ds_write_b128 v35, v[36:39] offset:48
	s_and_saveexec_b64 s[0:1], s[8:9]
	s_cbranch_execz .LBB0_186
	s_ashr_i32 s3, s2, 31
	v_add_u32_e32 v34, 0xffffff80, v34
	v_mov_b32_e32 v35, v1
	s_lshl_b64 s[8:9], s[2:3], 9
	v_lshl_add_u64 v[34:35], v[34:35], 2, s[8:9]
	v_or_b32_e32 v34, s10, v34
	v_readlane_b32 s8, v254, 53
	v_lshlrev_b64 v[34:35], 8, v[34:35]
	v_readlane_b32 s9, v254, 54
	s_nop 1
	v_lshl_add_u64 v[34:35], s[8:9], 0, v[34:35]
	v_lshl_add_u64 v[34:35], v[0:1], 2, v[34:35]
	global_store_dwordx4 v[34:35], v[14:17], off
	global_store_dwordx4 v[34:35], v[10:13], off offset:16
	global_store_dwordx4 v[34:35], v[6:9], off offset:32
	global_store_dwordx4 v[34:35], v[2:5], off offset:48
	global_store_dwordx4 v[34:35], v[30:33], off offset:64
	global_store_dwordx4 v[34:35], v[26:29], off offset:80
	global_store_dwordx4 v[34:35], v[22:25], off offset:96
	global_store_dwordx4 v[34:35], v[18:21], off offset:112
.LBB0_186:
	s_or_b64 exec, exec, s[0:1]
	v_and_b32_e32 v0, 0xff, v88
	s_movk_i32 s0, 0x7f
	v_ashrrev_i32_e32 v2, 8, v88
	v_cmp_lt_u32_e64 s[0:1], s0, v0
	s_nor_b64 s[8:9], s[4:5], s[0:1]
	v_lshlrev_b32_e32 v34, 5, v2
	s_and_saveexec_b64 s[12:13], s[8:9]
	s_xor_b64 s[8:9], exec, s[12:13]
	v_lshlrev_b32_e32 v34, 5, v2
	s_or_saveexec_b64 s[8:9], s[8:9]
	v_mov_b32_e32 v9, 0
	v_mov_b32_e32 v8, 0
	v_mov_b32_e32 v7, 0
	v_mov_b32_e32 v6, 0
	v_mov_b32_e32 v21, 0
	v_mov_b32_e32 v20, 0
	v_mov_b32_e32 v19, 0
	v_mov_b32_e32 v18, 0
	v_mov_b32_e32 v5, 0
	v_mov_b32_e32 v4, 0
	v_mov_b32_e32 v3, 0
	v_mov_b32_e32 v2, 0
	v_mov_b32_e32 v13, 0
	v_mov_b32_e32 v12, 0
	v_mov_b32_e32 v11, 0
	v_mov_b32_e32 v10, 0
	v_mov_b32_e32 v17, 0
	v_mov_b32_e32 v16, 0
	v_mov_b32_e32 v15, 0
	v_mov_b32_e32 v14, 0
	v_mov_b32_e32 v25, 0
	v_mov_b32_e32 v24, 0
	v_mov_b32_e32 v23, 0
	v_mov_b32_e32 v22, 0
	v_mov_b32_e32 v29, 0
	v_mov_b32_e32 v28, 0
	v_mov_b32_e32 v27, 0
	v_mov_b32_e32 v26, 0
	v_mov_b32_e32 v33, 0
	v_mov_b32_e32 v32, 0
	v_mov_b32_e32 v31, 0
	v_mov_b32_e32 v30, 0
	s_xor_b64 exec, exec, s[8:9]
	s_cbranch_execz .LBB0_190
	s_add_u32 s12, s78, 0xffffff80
	s_addc_u32 s13, s79, -1
	v_lshl_add_u64 v[2:3], s[12:13], 0, v[0:1]
	v_readlane_b32 s12, v254, 32
	v_readlane_b32 s13, v254, 33
	s_lshl_b32 s92, s10, 7
	v_ashrrev_i32_e32 v35, 31, v34
	v_mov_b64_e32 v[4:5], s[12:13]
	v_mad_u64_u32 v[4:5], s[12:13], v2, s95, v[4:5]
	v_mad_i32_i24 v5, v3, s95, v5
	v_lshl_add_u64 v[2:3], v[4:5], 0, s[92:93]
	v_lshl_add_u64 v[10:11], v[34:35], 1, v[2:3]
	s_mov_b64 s[12:13], 0x1200
	s_movk_i32 s3, 0x1000
	v_lshl_add_u64 v[12:13], v[10:11], 0, s[12:13]
	v_add_co_u32_e32 v10, vcc, s3, v10
	v_mov_b64_e32 v[2:3], v[184:185]
	v_mov_b64_e32 v[4:5], v[186:187]
	v_mov_b64_e32 v[6:7], v[188:189]
	v_mov_b64_e32 v[8:9], v[190:191]
	v_addc_co_u32_e32 v11, vcc, 0, v11, vcc
	v_mov_b64_e32 v[18:19], v[180:181]
	v_mov_b64_e32 v[20:21], v[182:183]
	v_mov_b64_e32 v[36:37], v[192:193]
	v_mov_b64_e32 v[38:39], v[194:195]
	v_lshlrev_b32_e32 v22, 16, v2
	v_and_b32_e32 v23, 0xffff0000, v2
	v_lshlrev_b32_e32 v24, 16, v3
	v_and_b32_e32 v25, 0xffff0000, v3
	v_lshlrev_b32_e32 v14, 16, v4
	v_and_b32_e32 v15, 0xffff0000, v4
	v_lshlrev_b32_e32 v16, 16, v5
	v_and_b32_e32 v17, 0xffff0000, v5
	v_lshlrev_b32_e32 v10, 16, v6
	v_and_b32_e32 v11, 0xffff0000, v6
	v_lshlrev_b32_e32 v12, 16, v7
	v_and_b32_e32 v13, 0xffff0000, v7
	v_lshlrev_b32_e32 v2, 16, v8
	v_and_b32_e32 v3, 0xffff0000, v8
	v_lshlrev_b32_e32 v4, 16, v9
	v_and_b32_e32 v5, 0xffff0000, v9
	v_lshlrev_b32_e32 v30, 16, v18
	v_and_b32_e32 v31, 0xffff0000, v18
	v_lshlrev_b32_e32 v32, 16, v19
	v_and_b32_e32 v33, 0xffff0000, v19
	v_lshlrev_b32_e32 v26, 16, v20
	v_and_b32_e32 v27, 0xffff0000, v20
	v_lshlrev_b32_e32 v28, 16, v21
	v_and_b32_e32 v29, 0xffff0000, v21
	v_lshlrev_b32_e32 v18, 16, v36
	v_and_b32_e32 v19, 0xffff0000, v36
	v_lshlrev_b32_e32 v20, 16, v37
	v_and_b32_e32 v21, 0xffff0000, v37
	v_lshlrev_b32_e32 v6, 16, v38
	v_and_b32_e32 v7, 0xffff0000, v38
	v_lshlrev_b32_e32 v8, 16, v39
	v_and_b32_e32 v9, 0xffff0000, v39

.LBB0_192:
	s_or_b64 exec, exec, s[0:1]
	v_readlane_b32 s2, v254, 32
	s_lshl_b32 s0, s10, 2
	v_readlane_b32 s1, v254, 41
	v_readlane_b32 s3, v254, 33
	v_lshlrev_b32_e32 v96, 3, v69
	v_ashrrev_i32_e32 v97, 31, v96
	v_lshlrev_b64 v[6:7], 1, v[96:97]
	v_lshlrev_b32_e32 v50, 2, v69
	v_xor_b32_e32 v77, 32, v211
	v_or_b32_e32 v51, 0x80, v106
	v_lshl_add_u32 v4, v88, 2, 0
	v_or_b32_e32 v5, s78, v106
	s_add_i32 s0, s0, s1
	v_mov_b64_e32 v[2:3], s[2:3]
	v_add_u32_e32 v12, 0x11c00, v4
	v_or_b32_e32 v4, s88, v5
	v_or_b32_e32 v8, s89, v5
	v_or_b32_e32 v10, s90, v5
	v_or_b32_e32 v13, s91, v5
	s_lshl_b32 s2, s0, 6
	v_mad_u64_u32 v[4:5], s[6:7], v4, s95, v[2:3]
	v_mad_u64_u32 v[8:9], s[6:7], v8, s95, v[2:3]
	v_mad_u64_u32 v[10:11], s[6:7], v10, s95, v[2:3]
	v_mad_u64_u32 v[2:3], s[6:7], v13, s95, v[2:3]
	s_ashr_i32 s3, s2, 31
	v_mad_i32_i24 v5, s79, v210, v5
	v_mad_i32_i24 v9, s79, v210, v9
	v_mad_i32_i24 v11, s79, v210, v11
	s_lshl_b64 s[6:7], s[2:3], 1
	v_mad_i32_i24 v3, s79, v210, v3
	v_lshl_add_u64 v[4:5], v[4:5], 0, s[6:7]
	v_lshl_add_u64 v[8:9], v[8:9], 0, s[6:7]
	v_lshl_add_u64 v[10:11], v[10:11], 0, s[6:7]
	v_lshl_add_u64 v[2:3], v[2:3], 0, s[6:7]
	v_lshl_add_u64 v[4:5], v[4:5], 0, v[6:7]
	v_lshl_add_u64 v[8:9], v[8:9], 0, v[6:7]
	v_lshl_add_u64 v[10:11], v[10:11], 0, v[6:7]
	v_lshl_add_u64 v[2:3], v[2:3], 0, v[6:7]
	v_readlane_b32 s1, v253, 22
	s_waitcnt vmcnt(0)
	ds_write_b32 v12, v175
	s_waitcnt lgkmcnt(0)
	s_barrier
	global_load_dwordx4 v[34:37], v[4:5], off offset:2112
	global_load_dwordx4 v[38:41], v[8:9], off offset:2112
	global_load_dwordx4 v[42:45], v[10:11], off offset:2112
	global_load_dwordx4 v[46:49], v[2:3], off offset:2112
	global_load_dwordx4 v[30:33], v[4:5], off offset:2048
	global_load_dwordx4 v[26:29], v[8:9], off offset:2048
	global_load_dwordx4 v[22:25], v[10:11], off offset:2048
	global_load_dwordx4 v[18:21], v[2:3], off offset:2048
	v_mov_b32_e32 v0, s1
	v_readlane_b32 s1, v253, 23
	v_xor_b32_e32 v2, 16, v211
	v_cmp_lt_i32_e32 vcc, v2, v76
	v_mov_b32_e32 v4, s1
	s_ashr_i32 s1, s0, 31
	v_cndmask_b32_e32 v6, v211, v2, vcc
	ds_read_b64 v[2:3], v0
	ds_read_b64 v[4:5], v4
	s_lshl_b64 s[0:1], s[0:1], 2
	v_lshlrev_b32_e32 v107, 2, v6
	v_cmp_lt_i32_e32 vcc, v77, v76
	s_waitcnt lgkmcnt(1)
	v_lshl_add_u64 v[2:3], v[2:3], 0, s[0:1]
	s_waitcnt lgkmcnt(0)
	v_lshl_add_u64 v[14:15], v[96:97], 2, v[4:5]
	global_load_dword v97, v[2:3], off
	s_nop 0
	global_load_dwordx4 v[2:5], v[14:15], off offset:144
	global_load_dwordx4 v[10:13], v[14:15], off offset:128
	global_load_dwordx4 v[6:9], v[14:15], off offset:16
	s_nop 0
	global_load_dwordx4 v[14:17], v[14:15], off
	v_cndmask_b32_e32 v0, v211, v77, vcc
	s_waitcnt vmcnt(9)
	v_lshlrev_b32_e32 v52, 16, v49
	v_lshlrev_b32_e32 v104, 16, v37
	v_and_b32_e32 v105, 0xffff0000, v37
	v_lshlrev_b32_e32 v86, 16, v41
	v_and_b32_e32 v87, 0xffff0000, v41
	s_waitcnt vmcnt(8)
	v_lshlrev_b32_e32 v100, 16, v33
	v_and_b32_e32 v101, 0xffff0000, v33
	s_waitcnt vmcnt(6)
	v_lshlrev_b32_e32 v64, 16, v25
	v_and_b32_e32 v65, 0xffff0000, v25
	v_lshlrev_b32_e32 v102, 16, v36
	v_and_b32_e32 v103, 0xffff0000, v36
	v_lshlrev_b32_e32 v82, 16, v40
	v_and_b32_e32 v83, 0xffff0000, v40
	v_lshlrev_b32_e32 v36, 16, v32
	v_and_b32_e32 v37, 0xffff0000, v32
	v_lshlrev_b32_e32 v70, 16, v24
	v_and_b32_e32 v71, 0xffff0000, v24
	v_lshlrev_b32_e32 v24, 16, v35
	v_and_b32_e32 v25, 0xffff0000, v35
	v_lshlrev_b32_e32 v88, 16, v39
	v_and_b32_e32 v89, 0xffff0000, v39
	v_lshlrev_b32_e32 v74, 16, v43
	v_and_b32_e32 v75, 0xffff0000, v43
	v_lshlrev_b32_e32 v32, 16, v34
	v_and_b32_e32 v33, 0xffff0000, v34
	v_lshlrev_b32_e32 v92, 16, v38
	v_and_b32_e32 v93, 0xffff0000, v38
	v_lshlrev_b32_e32 v62, 16, v42
	v_and_b32_e32 v63, 0xffff0000, v42
	v_lshlrev_b32_e32 v42, 16, v46
	v_and_b32_e32 v43, 0xffff0000, v46
	v_lshlrev_b32_e32 v60, 16, v45
	v_and_b32_e32 v61, 0xffff0000, v45
	v_and_b32_e32 v53, 0xffff0000, v49
	v_lshlrev_b32_e32 v80, 16, v29
	v_and_b32_e32 v81, 0xffff0000, v29
	s_waitcnt vmcnt(5)
	v_lshlrev_b32_e32 v54, 16, v21
	v_and_b32_e32 v55, 0xffff0000, v21
	v_lshlrev_b32_e32 v68, 16, v44
	v_and_b32_e32 v69, 0xffff0000, v44
	v_lshlrev_b32_e32 v44, 16, v48
	v_and_b32_e32 v45, 0xffff0000, v48
	v_lshlrev_b32_e32 v84, 16, v28
	v_and_b32_e32 v85, 0xffff0000, v28
	v_lshlrev_b32_e32 v48, 16, v20
	v_and_b32_e32 v49, 0xffff0000, v20
	v_lshlrev_b32_e32 v56, 16, v47
	v_and_b32_e32 v57, 0xffff0000, v47
	v_lshlrev_b32_e32 v28, 16, v31
	v_and_b32_e32 v29, 0xffff0000, v31
	v_lshlrev_b32_e32 v90, 16, v27
	v_and_b32_e32 v91, 0xffff0000, v27
	v_lshlrev_b32_e32 v58, 16, v19
	v_and_b32_e32 v59, 0xffff0000, v19
	v_lshlrev_b32_e32 v34, 16, v30
	v_and_b32_e32 v35, 0xffff0000, v30
	v_lshlrev_b32_e32 v94, 16, v26
	v_and_b32_e32 v95, 0xffff0000, v26
	v_lshlrev_b32_e32 v72, 16, v22
	v_and_b32_e32 v73, 0xffff0000, v22
	v_lshlrev_b32_e32 v46, 16, v18
	v_and_b32_e32 v47, 0xffff0000, v18
	v_pk_mul_f32 v[18:19], v[104:105], v[104:105]
	v_pk_mul_f32 v[20:21], v[86:87], v[86:87]
	v_pk_mul_f32 v[30:31], v[102:103], v[102:103]
	v_pk_mul_f32 v[38:39], v[82:83], v[82:83]
	v_pk_mul_f32 v[98:99], v[24:25], v[24:25]
	v_pk_mul_f32 v[108:109], v[88:89], v[88:89]
	v_pk_mul_f32 v[114:115], v[32:33], v[32:33]
	v_pk_mul_f32 v[116:117], v[92:93], v[92:93]
	v_pk_mul_f32 v[118:119], v[62:63], v[62:63]
	v_pk_mul_f32 v[120:121], v[42:43], v[42:43]
	v_lshlrev_b32_e32 v66, 16, v23
	v_and_b32_e32 v67, 0xffff0000, v23
	v_pk_mul_f32 v[22:23], v[60:61], v[60:61]
	v_pk_mul_f32 v[26:27], v[52:53], v[52:53]
	v_pk_mul_f32 v[40:41], v[68:69], v[68:69]
	v_pk_mul_f32 v[78:79], v[44:45], v[44:45]
	v_pk_mul_f32 v[110:111], v[74:75], v[74:75]
	v_pk_mul_f32 v[112:113], v[56:57], v[56:57]
	v_pk_fma_f32 v[18:19], v[100:101], v[100:101], v[18:19]
	v_pk_fma_f32 v[20:21], v[80:81], v[80:81], v[20:21]
	v_pk_fma_f32 v[30:31], v[36:37], v[36:37], v[30:31]
	v_pk_fma_f32 v[38:39], v[84:85], v[84:85], v[38:39]
	v_pk_fma_f32 v[98:99], v[28:29], v[28:29], v[98:99]
	v_pk_fma_f32 v[108:109], v[90:91], v[90:91], v[108:109]
	v_pk_fma_f32 v[114:115], v[34:35], v[34:35], v[114:115]
	v_pk_fma_f32 v[116:117], v[94:95], v[94:95], v[116:117]
	v_pk_fma_f32 v[118:119], v[72:73], v[72:73], v[118:119]
	v_pk_fma_f32 v[120:121], v[46:47], v[46:47], v[120:121]
	v_pk_fma_f32 v[22:23], v[64:65], v[64:65], v[22:23]
	v_pk_fma_f32 v[26:27], v[54:55], v[54:55], v[26:27]
	v_pk_fma_f32 v[40:41], v[70:71], v[70:71], v[40:41]
	v_pk_fma_f32 v[78:79], v[48:49], v[48:49], v[78:79]
	v_pk_fma_f32 v[110:111], v[66:67], v[66:67], v[110:111]
	v_pk_fma_f32 v[112:113], v[58:59], v[58:59], v[112:113]
	v_mov_b32_e32 v122, v116
	v_mov_b32_e32 v123, v114
	v_mov_b32_e32 v114, v117
	v_mov_b32_e32 v116, v108
	v_mov_b32_e32 v117, v98
	v_mov_b32_e32 v98, v109
	v_mov_b32_e32 v108, v38
	v_mov_b32_e32 v109, v30
	v_mov_b32_e32 v30, v39
	v_mov_b32_e32 v38, v20
	v_mov_b32_e32 v39, v18
	v_mov_b32_e32 v18, v21
	v_mov_b32_e32 v20, v120
	v_mov_b32_e32 v21, v118
	v_mov_b32_e32 v118, v121
	v_mov_b32_e32 v120, v112
	v_mov_b32_e32 v121, v110
	v_mov_b32_e32 v110, v113
	v_mov_b32_e32 v112, v78
	v_mov_b32_e32 v113, v40
	v_mov_b32_e32 v40, v79
	v_mov_b32_e32 v78, v26
	v_mov_b32_e32 v79, v22
	v_mov_b32_e32 v22, v27
	v_pk_add_f32 v[26:27], v[122:123], v[114:115]
	v_pk_add_f32 v[20:21], v[20:21], v[118:119]
	v_pk_add_f32 v[26:27], v[116:117], v[26:27]
	v_pk_add_f32 v[20:21], v[120:121], v[20:21]
	v_pk_add_f32 v[26:27], v[98:99], v[26:27]
	v_pk_add_f32 v[20:21], v[110:111], v[20:21]
	v_pk_add_f32 v[26:27], v[108:109], v[26:27]
	v_pk_add_f32 v[20:21], v[112:113], v[20:21]
	v_pk_add_f32 v[26:27], v[30:31], v[26:27]
	v_pk_add_f32 v[20:21], v[40:41], v[20:21]
	v_pk_add_f32 v[26:27], v[38:39], v[26:27]
	v_pk_add_f32 v[20:21], v[78:79], v[20:21]
	v_pk_add_f32 v[18:19], v[18:19], v[26:27]
	v_pk_add_f32 v[20:21], v[22:23], v[20:21]
	ds_bpermute_b32 v23, v107, v19
	ds_bpermute_b32 v22, v107, v18
	ds_bpermute_b32 v27, v107, v21
	ds_bpermute_b32 v26, v107, v20
	v_lshlrev_b32_e32 v108, 2, v0
	v_sub_u32_e32 v0, v51, v50
	s_waitcnt lgkmcnt(2)
	v_pk_add_f32 v[18:19], v[18:19], v[22:23]
	v_cmp_gt_u32_e32 vcc, s94, v0
	s_waitcnt lgkmcnt(0)
	v_pk_add_f32 v[76:77], v[20:21], v[26:27]
	ds_bpermute_b32 v21, v108, v19
	ds_bpermute_b32 v20, v108, v18
	ds_bpermute_b32 v79, v108, v77
	ds_bpermute_b32 v78, v108, v76
	v_mov_b32_e32 v109, 0xf1c9f2ca
	v_sub_u32_e32 v22, v106, v50
	v_mov_b32_e32 v110, 0xf1c9f2ca
	s_and_saveexec_b64 s[0:1], vcc
	v_sub_u32_e32 v23, v106, v50
	v_lshl_add_u32 v23, v23, 2, s96
	ds_read_b32 v110, v23 offset:512
	s_or_b64 exec, exec, s[0:1]
	v_not_b32_e32 v23, v50
	v_add_u32_e32 v26, v51, v23
	v_cmp_gt_u32_e32 vcc, s94, v26
	s_and_saveexec_b64 s[0:1], vcc
	v_add_u32_e32 v23, v106, v23
	v_lshl_add_u32 v23, v23, 2, s96
	ds_read_b32 v109, v23 offset:512
	s_or_b64 exec, exec, s[0:1]
	v_or_b32_e32 v23, 2, v50
	v_sub_u32_e32 v26, v51, v23
	v_cmp_gt_u32_e32 vcc, s94, v26
	v_mov_b32_e32 v111, 0xf1c9f2ca
	v_mov_b32_e32 v112, 0xf1c9f2ca
	s_and_saveexec_b64 s[0:1], vcc
	v_sub_u32_e32 v23, v106, v23
	v_lshl_add_u32 v23, v23, 2, s96
	ds_read_b32 v112, v23 offset:512
	s_or_b64 exec, exec, s[0:1]
	v_or_b32_e32 v23, 3, v50
	v_sub_u32_e32 v26, v51, v23
	v_cmp_gt_u32_e32 vcc, s94, v26
	s_and_saveexec_b64 s[0:1], vcc
	v_sub_u32_e32 v23, v106, v23
	v_lshl_add_u32 v23, v23, 2, s96
	ds_read_b32 v111, v23 offset:512
	s_or_b64 exec, exec, s[0:1]
	v_add_u32_e32 v23, -16, v0
	v_cmp_gt_u32_e32 vcc, s94, v23
	v_mov_b32_e32 v113, 0xf1c9f2ca
	v_mov_b32_e32 v114, 0xf1c9f2ca
	s_and_saveexec_b64 s[0:1], vcc
	v_sub_u32_e32 v23, v106, v50
	v_lshl_add_u32 v23, v23, 2, s96
	ds_read_b32 v114, v23 offset:448
	s_or_b64 exec, exec, s[0:1]
	v_subrev_u32_e32 v23, 17, v0
	v_cmp_gt_u32_e32 vcc, s94, v23
	s_and_saveexec_b64 s[0:1], vcc
	v_sub_u32_e32 v23, v106, v50
	v_lshl_add_u32 v23, v23, 2, s96
	ds_read_b32 v113, v23 offset:444
	s_or_b64 exec, exec, s[0:1]
	v_subrev_u32_e32 v23, 18, v0
	v_cmp_gt_u32_e32 vcc, s94, v23
	v_mov_b32_e32 v115, 0xf1c9f2ca
	v_mov_b32_e32 v116, 0xf1c9f2ca
	s_and_saveexec_b64 s[0:1], vcc
	v_sub_u32_e32 v23, v106, v50
	v_lshl_add_u32 v23, v23, 2, s96
	ds_read_b32 v116, v23 offset:440
	s_or_b64 exec, exec, s[0:1]
	v_subrev_u32_e32 v23, 19, v0
	v_cmp_gt_u32_e32 vcc, s94, v23
	s_and_saveexec_b64 s[0:1], vcc
	v_sub_u32_e32 v23, v106, v50
	v_lshl_add_u32 v23, v23, 2, s96
	ds_read_b32 v115, v23 offset:436
	s_or_b64 exec, exec, s[0:1]
	v_subrev_u32_e32 v23, 32, v0
	v_cmp_gt_u32_e32 vcc, s94, v23
	v_mov_b32_e32 v117, 0xf1c9f2ca
	v_mov_b32_e32 v118, 0xf1c9f2ca
	s_and_saveexec_b64 s[0:1], vcc
	v_sub_u32_e32 v23, v106, v50
	v_lshl_add_u32 v23, v23, 2, s96
	ds_read_b32 v118, v23 offset:384
	s_or_b64 exec, exec, s[0:1]
	v_subrev_u32_e32 v23, 33, v0
	v_cmp_gt_u32_e32 vcc, s94, v23
	s_and_saveexec_b64 s[0:1], vcc
	v_sub_u32_e32 v23, v106, v50
	v_lshl_add_u32 v23, v23, 2, s96
	ds_read_b32 v117, v23 offset:380
	s_or_b64 exec, exec, s[0:1]
	v_subrev_u32_e32 v23, 34, v0
	v_cmp_gt_u32_e32 vcc, s94, v23
	v_mov_b32_e32 v119, 0xf1c9f2ca
	v_mov_b32_e32 v120, 0xf1c9f2ca
	s_and_saveexec_b64 s[0:1], vcc
	v_sub_u32_e32 v23, v106, v50
	v_lshl_add_u32 v23, v23, 2, s96
	ds_read_b32 v120, v23 offset:376
	s_or_b64 exec, exec, s[0:1]
	v_subrev_u32_e32 v23, 35, v0
	v_cmp_gt_u32_e32 vcc, s94, v23
	s_and_saveexec_b64 s[0:1], vcc
	v_sub_u32_e32 v23, v106, v50
	v_lshl_add_u32 v23, v23, 2, s96
	ds_read_b32 v119, v23 offset:372
	s_or_b64 exec, exec, s[0:1]
	v_subrev_u32_e32 v23, 48, v0
	v_cmp_gt_u32_e32 vcc, s94, v23
	v_mov_b32_e32 v121, 0xf1c9f2ca
	v_mov_b32_e32 v122, 0xf1c9f2ca
	s_and_saveexec_b64 s[0:1], vcc
	v_sub_u32_e32 v23, v106, v50
	v_lshl_add_u32 v23, v23, 2, s96
	ds_read_b32 v122, v23 offset:320
	s_or_b64 exec, exec, s[0:1]
	v_subrev_u32_e32 v23, 49, v0
	v_cmp_gt_u32_e32 vcc, s94, v23
	s_and_saveexec_b64 s[0:1], vcc
	v_sub_u32_e32 v23, v106, v50
	v_lshl_add_u32 v23, v23, 2, s96
	ds_read_b32 v121, v23 offset:316
	s_or_b64 exec, exec, s[0:1]
	v_subrev_u32_e32 v23, 50, v0
	v_cmp_gt_u32_e32 vcc, s94, v23
	v_mov_b32_e32 v123, 0xf1c9f2ca
	v_mov_b32_e32 v124, 0xf1c9f2ca
	s_and_saveexec_b64 s[0:1], vcc
	v_sub_u32_e32 v23, v106, v50
	v_lshl_add_u32 v23, v23, 2, s96
	ds_read_b32 v124, v23 offset:312
	s_or_b64 exec, exec, s[0:1]
	v_subrev_u32_e32 v23, 51, v0
	v_cmp_gt_u32_e32 vcc, s94, v23
	s_and_saveexec_b64 s[0:1], vcc
	v_sub_u32_e32 v23, v106, v50
	v_lshl_add_u32 v23, v23, 2, s96
	ds_read_b32 v123, v23 offset:308
	s_or_b64 exec, exec, s[0:1]
	v_subrev_u32_e32 v23, 64, v0
	v_cmp_gt_u32_e32 vcc, s94, v23
	v_mov_b32_e32 v125, 0xf1c9f2ca
	v_mov_b32_e32 v126, 0xf1c9f2ca
	s_and_saveexec_b64 s[0:1], vcc
	v_sub_u32_e32 v23, v106, v50
	v_lshl_add_u32 v23, v23, 2, s96
	ds_read_b32 v126, v23 offset:256
	s_or_b64 exec, exec, s[0:1]
	v_add_u32_e32 v23, 0xffffffbf, v0
	v_cmp_gt_u32_e32 vcc, s94, v23
	s_and_saveexec_b64 s[0:1], vcc
	v_sub_u32_e32 v23, v106, v50
	v_lshl_add_u32 v23, v23, 2, s96
	ds_read_b32 v125, v23 offset:252
	s_or_b64 exec, exec, s[0:1]
	v_add_u32_e32 v23, 0xffffffbe, v0
	v_cmp_gt_u32_e32 vcc, s94, v23
	v_mov_b32_e32 v127, 0xf1c9f2ca
	v_mov_b32_e32 v128, 0xf1c9f2ca
	s_and_saveexec_b64 s[0:1], vcc
	v_sub_u32_e32 v23, v106, v50
	v_lshl_add_u32 v23, v23, 2, s96
	ds_read_b32 v128, v23 offset:248
	s_or_b64 exec, exec, s[0:1]
	v_add_u32_e32 v23, 0xffffffbd, v0
	v_cmp_gt_u32_e32 vcc, s94, v23
	s_and_saveexec_b64 s[0:1], vcc
	v_sub_u32_e32 v23, v106, v50
	v_lshl_add_u32 v23, v23, 2, s96
	ds_read_b32 v127, v23 offset:244
	s_or_b64 exec, exec, s[0:1]
	v_add_u32_e32 v23, 0xffffffb0, v0
	v_cmp_gt_u32_e32 vcc, s94, v23
	v_mov_b32_e32 v129, 0xf1c9f2ca
	v_mov_b32_e32 v130, 0xf1c9f2ca
	s_and_saveexec_b64 s[0:1], vcc
	v_sub_u32_e32 v23, v106, v50
	v_lshl_add_u32 v23, v23, 2, s96
	ds_read_b32 v130, v23 offset:192
	s_or_b64 exec, exec, s[0:1]
	v_add_u32_e32 v23, 0xffffffaf, v0
	v_cmp_gt_u32_e32 vcc, s94, v23
	s_and_saveexec_b64 s[0:1], vcc
	v_sub_u32_e32 v23, v106, v50
	v_lshl_add_u32 v23, v23, 2, s96
	ds_read_b32 v129, v23 offset:188
	s_or_b64 exec, exec, s[0:1]
	v_add_u32_e32 v23, 0xffffffae, v0
	v_cmp_gt_u32_e32 vcc, s94, v23
	v_mov_b32_e32 v131, 0xf1c9f2ca
	v_mov_b32_e32 v132, 0xf1c9f2ca
	s_and_saveexec_b64 s[0:1], vcc
	v_sub_u32_e32 v23, v106, v50
	v_lshl_add_u32 v23, v23, 2, s96
	ds_read_b32 v132, v23 offset:184
	s_or_b64 exec, exec, s[0:1]
	v_add_u32_e32 v23, 0xffffffad, v0
	v_cmp_gt_u32_e32 vcc, s94, v23
	s_and_saveexec_b64 s[0:1], vcc
	v_sub_u32_e32 v23, v106, v50
	v_lshl_add_u32 v23, v23, 2, s96
	ds_read_b32 v131, v23 offset:180
	s_or_b64 exec, exec, s[0:1]
	v_add_u32_e32 v23, 0xffffffa0, v0
	v_cmp_gt_u32_e32 vcc, s94, v23
	v_mov_b32_e32 v133, 0xf1c9f2ca
	v_mov_b32_e32 v134, 0xf1c9f2ca
	s_and_saveexec_b64 s[0:1], vcc
	v_sub_u32_e32 v23, v106, v50
	v_lshl_add_u32 v23, v23, 2, s96
	ds_read_b32 v134, v23 offset:128
	s_or_b64 exec, exec, s[0:1]
	v_add_u32_e32 v23, 0xffffff9f, v0
	v_cmp_gt_u32_e32 vcc, s94, v23
	s_and_saveexec_b64 s[0:1], vcc
	v_sub_u32_e32 v23, v106, v50
	v_lshl_add_u32 v23, v23, 2, s96
	ds_read_b32 v133, v23 offset:124
	s_or_b64 exec, exec, s[0:1]
	v_add_u32_e32 v23, 0xffffff9e, v0
	v_cmp_gt_u32_e32 vcc, s94, v23
	v_mov_b32_e32 v135, 0xf1c9f2ca
	v_mov_b32_e32 v136, 0xf1c9f2ca
	s_and_saveexec_b64 s[0:1], vcc
	v_sub_u32_e32 v23, v106, v50
	v_lshl_add_u32 v23, v23, 2, s96
	ds_read_b32 v136, v23 offset:120
	s_or_b64 exec, exec, s[0:1]
	v_add_u32_e32 v23, 0xffffff9d, v0
	v_cmp_gt_u32_e32 vcc, s94, v23
	s_and_saveexec_b64 s[0:1], vcc
	v_sub_u32_e32 v23, v106, v50
	v_lshl_add_u32 v23, v23, 2, s96
	ds_read_b32 v135, v23 offset:116
	s_or_b64 exec, exec, s[0:1]
	v_add_u32_e32 v23, 0xffffff90, v0
	v_cmp_gt_u32_e32 vcc, s94, v23
	v_mov_b32_e32 v137, 0xf1c9f2ca
	v_mov_b32_e32 v138, 0xf1c9f2ca
	s_and_saveexec_b64 s[0:1], vcc
	v_sub_u32_e32 v23, v106, v50
	v_lshl_add_u32 v23, v23, 2, s96
	ds_read_b32 v138, v23 offset:64
	s_or_b64 exec, exec, s[0:1]
	v_add_u32_e32 v23, 0xffffff8f, v0
	v_cmp_gt_u32_e32 vcc, s94, v23
	s_and_saveexec_b64 s[0:1], vcc
	v_sub_u32_e32 v23, v106, v50
	v_lshl_add_u32 v23, v23, 2, s96
	ds_read_b32 v137, v23 offset:60
	s_or_b64 exec, exec, s[0:1]
	v_add_u32_e32 v23, 0xffffff8e, v0
	v_cmp_gt_u32_e32 vcc, s94, v23
	v_mov_b32_e32 v139, 0xf1c9f2ca
	s_and_saveexec_b64 s[0:1], vcc
	v_sub_u32_e32 v23, v106, v50
	v_lshl_add_u32 v23, v23, 2, s96
	ds_read_b32 v139, v23 offset:56
	s_or_b64 exec, exec, s[0:1]
	v_add_u32_e32 v23, 0xffffff8d, v0
	s_movk_i32 s0, 0x7f
	v_cmp_lt_u32_e32 vcc, s0, v23
	s_and_saveexec_b64 s[0:1], vcc
	s_xor_b64 s[0:1], exec, s[0:1]
	v_sub_u32_e32 v22, v106, v50
	s_or_saveexec_b64 s[0:1], s[0:1]
	v_mov_b32_e32 v140, 0xf1c9f2ca
	v_mov_b32_e32 v141, 0xf1c9f2ca
	s_xor_b64 exec, exec, s[0:1]
	v_lshl_add_u32 v23, v22, 2, s96
	ds_read_b32 v141, v23 offset:52
	s_or_b64 exec, exec, s[0:1]
	v_cmp_gt_u32_e32 vcc, s94, v22
	s_and_saveexec_b64 s[0:1], vcc
	v_lshl_add_u32 v23, v22, 2, s96
	ds_read_b32 v140, v23
	s_or_b64 exec, exec, s[0:1]
	v_add_u32_e32 v23, 0xffffff7f, v0
	v_cmp_gt_u32_e32 vcc, s94, v23
	v_mov_b32_e32 v142, 0xf1c9f2ca
	v_lshlrev_b32_e32 v22, 2, v22
	v_mov_b32_e32 v143, 0xf1c9f2ca
	s_and_saveexec_b64 s[0:1], vcc
	v_add3_u32 v23, v22, s96, -4
	ds_read_b32 v143, v23
	s_or_b64 exec, exec, s[0:1]
	v_add_u32_e32 v23, 0xffffff7e, v0
	v_cmp_gt_u32_e32 vcc, s94, v23
	s_and_saveexec_b64 s[0:1], vcc
	v_add3_u32 v23, v22, s96, -8
	ds_read_b32 v142, v23
	s_or_b64 exec, exec, s[0:1]
	v_add_u32_e32 v0, 0xffffff7d, v0
	v_cmp_gt_u32_e32 vcc, s94, v0
	v_mov_b32_e32 v144, 0xf1c9f2ca
	s_and_saveexec_b64 s[0:1], vcc
	v_add3_u32 v0, v22, s96, -12
	ds_read_b32 v144, v0
	s_or_b64 exec, exec, s[0:1]
	s_waitcnt lgkmcnt(2)
	v_pk_add_f32 v[18:19], v[18:19], v[20:21]
	s_mov_b32 s0, 0x3c800000
	v_pk_fma_f32 v[98:99], v[18:19], s[0:1], v[240:241] op_sel_hi:[1,0,0]
	s_mov_b32 s0, 0x800000
	v_mul_f32_e32 v0, 0x4b800000, v99
	v_cmp_gt_f32_e32 vcc, s0, v99
	v_readlane_b32 s10, v254, 43
	v_readlane_b32 s18, v254, 45
	v_cndmask_b32_e32 v0, v99, v0, vcc
	v_rsq_f32_e32 v0, v0
	v_lshlrev_b32_e32 v99, 1, v96
	v_cmp_gt_f32_e64 s[62:63], s0, v98
	s_and_b64 s[0:1], s[4:5], exec
	v_mul_f32_e32 v18, 0x45800000, v0
	v_cndmask_b32_e32 v0, v0, v18, vcc
	v_mul_f32_e32 v0, 0x3e000000, v0
	s_waitcnt vmcnt(3)
	v_pk_mul_f32 v[18:19], v[4:5], v[0:1] op_sel_hi:[1,0]
	s_waitcnt vmcnt(0)
	v_pk_mul_f32 v[22:23], v[16:17], v[0:1] op_sel_hi:[1,0]
	v_pk_mul_f32 v[18:19], v[18:19], v[104:105]
	v_pk_mul_f32 v[22:23], v[22:23], v[28:29]
	v_cvt_pk_bf16_f32 v21, v18, v19
	v_pk_mul_f32 v[18:19], v[8:9], v[0:1] op_sel_hi:[1,0]
	v_cvt_pk_bf16_f32 v39, v22, v23
	v_pk_mul_f32 v[18:19], v[18:19], v[100:101]
	v_pk_mul_f32 v[22:23], v[10:11], v[0:1] op_sel_hi:[1,0]
	v_cvt_pk_bf16_f32 v41, v18, v19
	v_pk_mul_f32 v[18:19], v[2:3], v[0:1] op_sel_hi:[1,0]
	v_pk_mul_f32 v[22:23], v[22:23], v[32:33]
	v_pk_mul_f32 v[18:19], v[18:19], v[102:103]
	s_cselect_b32 s92, 0, 0x80
	v_cvt_pk_bf16_f32 v20, v18, v19
	v_pk_mul_f32 v[18:19], v[6:7], v[0:1] op_sel_hi:[1,0]
	v_readlane_b32 s46, v255, 4
	v_pk_mul_f32 v[18:19], v[18:19], v[36:37]
	s_nop 0
	v_cvt_pk_bf16_f32 v40, v18, v19
	v_pk_mul_f32 v[18:19], v[12:13], v[0:1] op_sel_hi:[1,0]
	s_nop 0
	v_pk_mul_f32 v[18:19], v[18:19], v[24:25]
	s_nop 0
	v_cvt_pk_bf16_f32 v19, v18, v19
	v_cvt_pk_bf16_f32 v18, v22, v23
	v_pk_mul_f32 v[22:23], v[14:15], v[0:1] op_sel_hi:[1,0]
	v_or_b32_e32 v0, s88, v106
	v_mul_u32_u24_e32 v0, 0x90, v0
	v_pk_mul_f32 v[22:23], v[22:23], v[34:35]
	v_add3_u32 v0, 0, v0, v99
	v_cvt_pk_bf16_f32 v38, v22, v23
	ds_read_b128 v[22:25], v0
	ds_read_b128 v[26:29], v0 offset:64
	s_waitcnt lgkmcnt(1)
	v_mfma_f32_16x16x32_bf16 v[22:25], v[22:25], v[38:41], 0
	v_or_b32_e32 v0, s89, v106
	v_mul_u32_u24_e32 v0, 0x90, v0
	v_add3_u32 v146, 0, v0, v99
	s_waitcnt lgkmcnt(0)
	v_mfma_f32_16x16x32_bf16 v[148:151], v[26:29], v[18:21], v[22:25]
	ds_read_b128 v[26:29], v146 offset:64
	v_or_b32_e32 v0, s90, v106
	v_mul_u32_u24_e32 v0, 0x90, v0
	ds_read_b128 v[22:25], v146
	s_waitcnt lgkmcnt(0)
	v_mfma_f32_16x16x32_bf16 v[22:25], v[22:25], v[38:41], 0
	v_add3_u32 v145, 0, v0, v99
	v_or_b32_e32 v0, s91, v106
	v_mul_u32_u24_e32 v0, 0x90, v0
	v_mfma_f32_16x16x32_bf16 v[152:155], v[26:29], v[18:21], v[22:25]
	ds_read_b128 v[26:29], v145 offset:64
	v_add3_u32 v105, 0, v0, v99
	v_or_b32_e32 v0, s10, v106
	s_nop 0
	ds_read_b128 v[22:25], v145
	s_waitcnt lgkmcnt(0)
	v_mfma_f32_16x16x32_bf16 v[22:25], v[22:25], v[38:41], 0
	v_mul_u32_u24_e32 v0, 0x90, v0
	v_add3_u32 v100, 0, v0, v99
	v_or_b32_e32 v0, s18, v106
	v_mfma_f32_16x16x32_bf16 v[156:159], v[26:29], v[18:21], v[22:25]
	ds_read_b128 v[26:29], v105 offset:64
	v_mul_u32_u24_e32 v0, 0x90, v0
	v_add3_u32 v101, 0, v0, v99
	s_nop 0
	ds_read_b128 v[22:25], v105
	s_waitcnt lgkmcnt(0)
	v_mfma_f32_16x16x32_bf16 v[22:25], v[22:25], v[38:41], 0
	v_or_b32_e32 v0, s73, v106
	v_mul_u32_u24_e32 v0, 0x90, v0
	v_add3_u32 v102, 0, v0, v99
	v_mfma_f32_16x16x32_bf16 v[160:163], v[26:29], v[18:21], v[22:25]
	ds_read_b128 v[26:29], v100 offset:64
	v_or_b32_e32 v0, s74, v106
	v_mul_u32_u24_e32 v0, 0x90, v0
	s_nop 0
	ds_read_b128 v[22:25], v100
	s_waitcnt lgkmcnt(0)
	v_mfma_f32_16x16x32_bf16 v[22:25], v[22:25], v[38:41], 0
	v_add3_u32 v103, 0, v0, v99
	ds_read_b128 v[170:173], v103 offset:64
	v_or_b32_e32 v0, s75, v106
	v_mfma_f32_16x16x32_bf16 v[34:37], v[26:29], v[18:21], v[22:25]
	ds_read_b128 v[26:29], v101 offset:64
	v_mul_u32_u24_e32 v0, 0x90, v0
	v_add3_u32 v104, 0, v0, v99
	s_nop 0
	ds_read_b128 v[22:25], v101
	s_waitcnt lgkmcnt(0)
	v_mfma_f32_16x16x32_bf16 v[22:25], v[22:25], v[38:41], 0
	v_add_u32_e32 v0, s88, v50
	v_cmp_le_i32_e32 vcc, s92, v0
	v_or_b32_e32 v51, 2, v0
	v_mfma_f32_16x16x32_bf16 v[30:33], v[26:29], v[18:21], v[22:25]
	ds_read_b128 v[26:29], v102 offset:64
	v_add_f32_e32 v147, v114, v152
	v_add_f32_e32 v152, v117, v157
	s_nop 0
	ds_read_b128 v[22:25], v102
	s_waitcnt lgkmcnt(0)
	v_mfma_f32_16x16x32_bf16 v[22:25], v[22:25], v[38:41], 0
	v_max_f32_e32 v147, 0xf149f2ca, v147
	v_max_f32_e32 v152, 0xf149f2ca, v152
	v_add_f32_e32 v34, v126, v34
	v_mfma_f32_16x16x32_bf16 v[26:29], v[26:29], v[18:21], v[22:25]
	v_add_f32_e32 v35, v125, v35
	v_max_f32_e32 v34, 0xf149f2ca, v34
	v_max_f32_e32 v35, 0xf149f2ca, v35
	s_nop 0
	ds_read_b128 v[22:25], v103
	s_waitcnt lgkmcnt(0)
	v_mfma_f32_16x16x32_bf16 v[22:25], v[22:25], v[38:41], 0
	v_add_f32_e32 v36, v128, v36
	v_add_f32_e32 v37, v127, v37
	v_max_f32_e32 v36, 0xf149f2ca, v36
	v_mfma_f32_16x16x32_bf16 v[22:25], v[170:173], v[18:21], v[22:25]
	ds_read_b128 v[170:173], v104
	v_max_f32_e32 v37, 0xf149f2ca, v37
	v_add_f32_e32 v30, v130, v30
	s_waitcnt lgkmcnt(0)
	v_mfma_f32_16x16x32_bf16 v[38:41], v[170:173], v[38:41], 0
	ds_read_b128 v[170:173], v104 offset:64
	v_add_f32_e32 v31, v129, v31
	v_max_f32_e32 v30, 0xf149f2ca, v30
	s_waitcnt lgkmcnt(0)
	v_mfma_f32_16x16x32_bf16 v[18:21], v[170:173], v[18:21], v[38:41]
	s_nop 2
	v_add_f32_e32 v38, v110, v148
	v_max_f32_e32 v38, 0xf149f2ca, v38
	v_cndmask_b32_e32 v39, v212, v38, vcc
	v_add_f32_e32 v38, v109, v149
	v_or_b32_e32 v40, 1, v0
	v_max_f32_e32 v38, 0xf149f2ca, v38
	v_cmp_le_i32_e32 vcc, s92, v40
	v_add_f32_e32 v41, v112, v150
	v_max_f32_e32 v41, 0xf149f2ca, v41
	v_cndmask_b32_e32 v40, v212, v38, vcc
	v_cmp_le_i32_e32 vcc, s92, v51
	v_or_b32_e32 v0, 3, v0
	v_add_f32_e32 v148, v113, v153
	v_cndmask_b32_e32 v51, v212, v41, vcc
	v_add_f32_e32 v41, v111, v151
	v_max_f32_e32 v41, 0xf149f2ca, v41
	v_cmp_le_i32_e32 vcc, s92, v0
	v_max3_f32 v38, v97, v39, v40
	v_max_f32_e32 v148, 0xf149f2ca, v148
	v_cndmask_b32_e32 v0, v212, v41, vcc
	v_add_u32_e32 v41, s89, v50
	v_or_b32_e32 v150, 2, v41
	v_cmp_gt_i32_e64 s[64:65], s92, v41
	v_or_b32_e32 v149, 1, v41
	v_cmp_gt_i32_e64 s[68:69], s92, v150
	v_add_f32_e32 v150, v115, v155
	v_or_b32_e32 v41, 3, v41
	v_cmp_gt_i32_e64 s[70:71], s92, v41
	v_max_f32_e32 v41, 0xf149f2ca, v150
	v_cmp_gt_i32_e64 s[66:67], s92, v149
	v_cndmask_b32_e64 v150, v41, v212, s[70:71]
	v_add_u32_e32 v41, s90, v50
	v_add_f32_e32 v149, v116, v154
	v_or_b32_e32 v154, 2, v41
	v_cmp_gt_i32_e64 s[54:55], s92, v41
	v_or_b32_e32 v153, 1, v41
	v_cmp_gt_i32_e64 s[58:59], s92, v154
	v_add_f32_e32 v154, v119, v159
	v_or_b32_e32 v41, 3, v41
	v_cmp_gt_i32_e64 s[60:61], s92, v41
	v_max_f32_e32 v41, 0xf149f2ca, v154
	v_cmp_gt_i32_e64 s[56:57], s92, v153
	v_cndmask_b32_e64 v154, v41, v212, s[60:61]
	v_add_u32_e32 v41, s91, v50
	v_add_f32_e32 v153, v120, v158
	v_or_b32_e32 v158, 2, v41
	v_cmp_gt_i32_e64 s[0:1], s92, v41
	v_or_b32_e32 v157, 1, v41
	v_cmp_gt_i32_e64 s[6:7], s92, v158
	v_add_f32_e32 v158, v123, v163
	v_or_b32_e32 v41, 3, v41
	v_cmp_gt_i32_e64 s[8:9], s92, v41
	v_max_f32_e32 v41, 0xf149f2ca, v158
	v_max3_f32 v38, v38, v51, v0
	v_cndmask_b32_e64 v158, v41, v212, s[8:9]
	v_add_u32_e32 v41, s10, v50
	v_or_b32_e32 v159, 1, v41
	v_cmp_gt_i32_e64 s[10:11], s92, v41
	v_cmp_gt_i32_e64 s[12:13], s92, v159
	v_or_b32_e32 v159, 2, v41
	v_or_b32_e32 v41, 3, v41
	v_cmp_gt_i32_e64 s[16:17], s92, v41
	v_add_u32_e32 v41, s18, v50
	v_cndmask_b32_e64 v147, v147, v212, s[64:65]
	v_cndmask_b32_e64 v148, v148, v212, s[66:67]
	v_max_f32_e32 v149, 0xf149f2ca, v149
	v_add_f32_e32 v151, v118, v156
	v_cmp_gt_i32_e64 s[14:15], s92, v159
	v_or_b32_e32 v159, 1, v41
	v_max3_f32 v38, v38, v147, v148
	v_cndmask_b32_e64 v149, v149, v212, s[68:69]
	v_max_f32_e32 v151, 0xf149f2ca, v151
	v_cmp_gt_i32_e64 s[18:19], s92, v41
	v_cmp_gt_i32_e64 s[20:21], s92, v159
	v_or_b32_e32 v159, 2, v41
	v_or_b32_e32 v41, 3, v41
	v_max3_f32 v38, v38, v149, v150
	v_cndmask_b32_e64 v151, v151, v212, s[54:55]
	v_cndmask_b32_e64 v152, v152, v212, s[56:57]
	v_max_f32_e32 v153, 0xf149f2ca, v153
	v_add_f32_e32 v155, v122, v160
	v_add_f32_e32 v156, v121, v161
	v_cmp_gt_i32_e64 s[24:25], s92, v41
	v_add_u32_e32 v41, s73, v50
	v_max3_f32 v38, v38, v151, v152
	v_cndmask_b32_e64 v153, v153, v212, s[58:59]
	v_max_f32_e32 v155, 0xf149f2ca, v155
	v_cmp_gt_i32_e64 s[4:5], s92, v157
	v_max_f32_e32 v156, 0xf149f2ca, v156
	v_add_f32_e32 v157, v124, v162
	v_cmp_gt_i32_e64 s[22:23], s92, v159
	v_or_b32_e32 v159, 1, v41
	v_max3_f32 v38, v38, v153, v154
	v_cndmask_b32_e64 v155, v155, v212, s[0:1]
	v_cndmask_b32_e64 v156, v156, v212, s[4:5]
	v_max_f32_e32 v157, 0xf149f2ca, v157
	v_cmp_gt_i32_e64 s[26:27], s92, v41
	v_cmp_gt_i32_e64 s[28:29], s92, v159
	v_or_b32_e32 v159, 2, v41
	v_or_b32_e32 v41, 3, v41
	v_max3_f32 v38, v38, v155, v156
	v_cndmask_b32_e64 v157, v157, v212, s[6:7]
	v_cmp_gt_i32_e64 s[34:35], s92, v41
	v_add_u32_e32 v41, s74, v50
	v_max3_f32 v38, v38, v157, v158
	v_cndmask_b32_e64 v34, v34, v212, s[10:11]
	v_cndmask_b32_e64 v35, v35, v212, s[12:13]
	v_cmp_gt_i32_e64 s[30:31], s92, v159
	v_or_b32_e32 v159, 1, v41
	v_max3_f32 v38, v38, v34, v35
	v_cndmask_b32_e64 v36, v36, v212, s[14:15]
	v_cndmask_b32_e64 v37, v37, v212, s[16:17]
	v_max_f32_e32 v31, 0xf149f2ca, v31
	v_add_f32_e32 v32, v132, v32
	v_add_f32_e32 v33, v131, v33
	v_cmp_gt_i32_e64 s[36:37], s92, v41
	v_cmp_gt_i32_e64 s[38:39], s92, v159
	v_or_b32_e32 v159, 2, v41
	v_or_b32_e32 v41, 3, v41
	v_max3_f32 v38, v38, v36, v37
	v_cndmask_b32_e64 v30, v30, v212, s[18:19]
	v_cndmask_b32_e64 v31, v31, v212, s[20:21]
	v_max_f32_e32 v32, 0xf149f2ca, v32
	v_max_f32_e32 v33, 0xf149f2ca, v33
	v_add_f32_e32 v26, v134, v26
	v_add_f32_e32 v27, v133, v27
	v_cmp_gt_i32_e64 s[42:43], s92, v41
	v_add_u32_e32 v41, s75, v50
	v_add_f32_e32 v18, v140, v18
	v_max3_f32 v38, v38, v30, v31
	v_cndmask_b32_e64 v32, v32, v212, s[22:23]
	v_cndmask_b32_e64 v33, v33, v212, s[24:25]
	v_max_f32_e32 v26, 0xf149f2ca, v26
	v_max_f32_e32 v27, 0xf149f2ca, v27
	v_add_f32_e32 v28, v136, v28
	v_add_f32_e32 v29, v135, v29
	v_cmp_gt_i32_e64 s[44:45], s92, v41
	v_max_f32_e32 v18, 0xf149f2ca, v18
	v_max3_f32 v38, v38, v32, v33
	v_cndmask_b32_e64 v26, v26, v212, s[26:27]
	v_cndmask_b32_e64 v27, v27, v212, s[28:29]
	v_max_f32_e32 v28, 0xf149f2ca, v28
	v_max_f32_e32 v29, 0xf149f2ca, v29
	v_add_f32_e32 v22, v138, v22
	v_add_f32_e32 v23, v137, v23
	v_cmp_gt_i32_e64 s[40:41], s92, v159
	v_cndmask_b32_e64 v159, v18, v212, s[44:45]
	v_add_f32_e32 v18, v143, v19
	v_or_b32_e32 v19, 1, v41
	v_max3_f32 v38, v38, v26, v27
	v_cndmask_b32_e64 v28, v28, v212, s[30:31]
	v_cndmask_b32_e64 v29, v29, v212, s[34:35]
	v_max_f32_e32 v22, 0xf149f2ca, v22
	v_max_f32_e32 v23, 0xf149f2ca, v23
	v_add_f32_e32 v24, v139, v24
	v_add_f32_e32 v25, v141, v25
	v_cmp_gt_i32_e64 s[48:49], s92, v19
	v_add_f32_e32 v19, v142, v20
	v_or_b32_e32 v20, 2, v41
	v_max3_f32 v38, v38, v28, v29
	v_cndmask_b32_e64 v22, v22, v212, s[36:37]
	v_cndmask_b32_e64 v23, v23, v212, s[38:39]
	v_max_f32_e32 v24, 0xf149f2ca, v24
	v_max_f32_e32 v25, 0xf149f2ca, v25
	v_cmp_gt_i32_e64 s[50:51], s92, v20
	v_max_f32_e32 v19, 0xf149f2ca, v19
	v_max3_f32 v38, v38, v22, v23
	v_cndmask_b32_e64 v24, v24, v212, s[40:41]
	v_cndmask_b32_e64 v25, v25, v212, s[42:43]
	v_max_f32_e32 v18, 0xf149f2ca, v18
	v_cndmask_b32_e64 v161, v19, v212, s[50:51]
	v_add_f32_e32 v19, v144, v21
	v_or_b32_e32 v20, 3, v41
	v_max3_f32 v38, v38, v24, v25
	v_cndmask_b32_e64 v160, v18, v212, s[48:49]
	v_cmp_gt_i32_e64 s[52:53], s92, v20
	v_max_f32_e32 v19, 0xf149f2ca, v19
	v_max3_f32 v18, v38, v159, v160
	v_cndmask_b32_e64 v162, v19, v212, s[52:53]
	v_max3_f32 v18, v18, v161, v162
	ds_bpermute_b32 v19, v107, v18
	s_andn2_b64 vcc, exec, s[76:77]
	s_waitcnt lgkmcnt(0)
	v_max_f32_e32 v19, v19, v19
	v_max_f32_e32 v18, v18, v19
	ds_bpermute_b32 v19, v108, v18
	s_waitcnt lgkmcnt(0)
	v_max_f32_e32 v19, v19, v19
	v_max_f32_e32 v41, v18, v19
	v_mul_u32_u24_e32 v18, 0x150, v106
	v_add3_u32 v38, s46, v18, v96
	v_sub_f32_e32 v18, v39, v41
	v_mul_f32_e32 v18, 0x3fb8aa3b, v18
	v_sub_f32_e32 v20, v40, v41
	v_exp_f32_e32 v18, v18
	v_mul_f32_e32 v20, 0x3fb8aa3b, v20
	v_sub_f32_e32 v21, v51, v41
	v_exp_f32_e32 v20, v20
	v_mul_f32_e32 v21, 0x3fb8aa3b, v21
	v_sub_f32_e32 v0, v0, v41
	v_exp_f32_e32 v21, v21
	v_mul_f32_e32 v0, 0x3fb8aa3b, v0
	v_exp_f32_e32 v0, v0
	v_add_f32_e32 v19, 0, v18
	v_add_f32_e32 v19, v20, v19
	v_add_f32_e32 v19, v21, v19
	v_add_f32_e32 v39, v0, v19
	v_cvt_pk_bf16_f32 v19, v21, v0
	v_sub_f32_e32 v0, v147, v41
	v_mul_f32_e32 v0, 0x3fb8aa3b, v0
	v_exp_f32_e32 v0, v0
	v_sub_f32_e32 v21, v148, v41
	v_cvt_pk_bf16_f32 v18, v18, v20
	v_mul_f32_e32 v21, 0x3fb8aa3b, v21
	v_add_f32_e32 v20, v0, v39
	v_sub_f32_e32 v39, v149, v41
	v_exp_f32_e32 v21, v21
	v_mul_f32_e32 v39, 0x3fb8aa3b, v39
	v_sub_f32_e32 v40, v150, v41
	v_exp_f32_e32 v39, v39
	v_mul_f32_e32 v40, 0x3fb8aa3b, v40
	v_exp_f32_e32 v40, v40
	v_add_f32_e32 v20, v21, v20
	v_add_f32_e32 v20, v39, v20
	v_readlane_b32 s46, v254, 47
	v_add_f32_e32 v51, v40, v20
	v_cvt_pk_bf16_f32 v20, v0, v21
	v_cvt_pk_bf16_f32 v21, v39, v40
	v_sub_f32_e32 v0, v151, v41
	ds_write2_b64 v38, v[18:19], v[20:21] offset1:4
	v_mul_f32_e32 v0, 0x3fb8aa3b, v0
	v_sub_f32_e32 v19, v152, v41
	v_exp_f32_e32 v0, v0
	v_mul_f32_e32 v19, 0x3fb8aa3b, v19
	v_sub_f32_e32 v20, v153, v41
	v_exp_f32_e32 v19, v19
	v_mul_f32_e32 v20, 0x3fb8aa3b, v20
	v_sub_f32_e32 v21, v154, v41
	v_exp_f32_e32 v20, v20
	v_mul_f32_e32 v21, 0x3fb8aa3b, v21
	v_exp_f32_e32 v21, v21
	v_add_f32_e32 v18, v0, v51
	v_add_f32_e32 v18, v19, v18
	v_add_f32_e32 v18, v20, v18
	v_add_f32_e32 v39, v21, v18
	v_cvt_pk_bf16_f32 v18, v0, v19
	v_sub_f32_e32 v0, v155, v41
	v_mul_f32_e32 v0, 0x3fb8aa3b, v0
	v_exp_f32_e32 v0, v0
	v_cvt_pk_bf16_f32 v19, v20, v21
	v_sub_f32_e32 v21, v156, v41
	v_mul_f32_e32 v21, 0x3fb8aa3b, v21
	v_add_f32_e32 v20, v0, v39
	v_sub_f32_e32 v39, v157, v41
	v_exp_f32_e32 v21, v21
	v_mul_f32_e32 v39, 0x3fb8aa3b, v39
	v_sub_f32_e32 v40, v158, v41
	v_exp_f32_e32 v39, v39
	v_mul_f32_e32 v40, 0x3fb8aa3b, v40
	v_exp_f32_e32 v40, v40
	v_add_f32_e32 v20, v21, v20
	v_add_f32_e32 v20, v39, v20
	v_add_f32_e32 v51, v40, v20
	v_cvt_pk_bf16_f32 v20, v0, v21
	v_cvt_pk_bf16_f32 v21, v39, v40
	v_sub_f32_e32 v0, v34, v41
	ds_write2_b64 v38, v[18:19], v[20:21] offset0:8 offset1:12
	v_mul_f32_e32 v0, 0x3fb8aa3b, v0
	v_sub_f32_e32 v19, v35, v41
	v_exp_f32_e32 v0, v0
	v_mul_f32_e32 v19, 0x3fb8aa3b, v19
	v_sub_f32_e32 v20, v36, v41
	v_exp_f32_e32 v19, v19
	v_mul_f32_e32 v20, 0x3fb8aa3b, v20
	v_sub_f32_e32 v21, v37, v41
	v_exp_f32_e32 v20, v20
	v_mul_f32_e32 v21, 0x3fb8aa3b, v21
	v_exp_f32_e32 v21, v21
	v_add_f32_e32 v18, v0, v51
	v_add_f32_e32 v18, v19, v18
	v_add_f32_e32 v18, v20, v18
	v_add_f32_e32 v34, v21, v18
	v_cvt_pk_bf16_f32 v18, v0, v19
	v_sub_f32_e32 v0, v30, v41
	v_cvt_pk_bf16_f32 v19, v20, v21
	v_mul_f32_e32 v0, 0x3fb8aa3b, v0
	v_sub_f32_e32 v21, v31, v41
	v_exp_f32_e32 v0, v0
	v_mul_f32_e32 v21, 0x3fb8aa3b, v21
	v_sub_f32_e32 v30, v32, v41
	v_exp_f32_e32 v21, v21
	v_mul_f32_e32 v30, 0x3fb8aa3b, v30
	v_sub_f32_e32 v31, v33, v41
	v_exp_f32_e32 v30, v30
	v_mul_f32_e32 v31, 0x3fb8aa3b, v31
	v_exp_f32_e32 v31, v31
	v_add_f32_e32 v20, v0, v34
	v_add_f32_e32 v20, v21, v20
	v_add_f32_e32 v20, v30, v20
	v_add_f32_e32 v32, v31, v20
	v_cvt_pk_bf16_f32 v20, v0, v21
	v_cvt_pk_bf16_f32 v21, v30, v31
	v_sub_f32_e32 v0, v26, v41
	ds_write2_b64 v38, v[18:19], v[20:21] offset0:16 offset1:20
	v_mul_f32_e32 v0, 0x3fb8aa3b, v0
	v_sub_f32_e32 v19, v27, v41
	v_exp_f32_e32 v0, v0
	v_mul_f32_e32 v19, 0x3fb8aa3b, v19
	v_sub_f32_e32 v20, v28, v41
	v_exp_f32_e32 v19, v19
	v_mul_f32_e32 v20, 0x3fb8aa3b, v20
	v_sub_f32_e32 v21, v29, v41
	v_exp_f32_e32 v20, v20
	v_mul_f32_e32 v21, 0x3fb8aa3b, v21
	v_exp_f32_e32 v21, v21
	v_add_f32_e32 v18, v0, v32
	v_add_f32_e32 v18, v19, v18
	v_add_f32_e32 v18, v20, v18
	v_add_f32_e32 v26, v21, v18
	v_cvt_pk_bf16_f32 v18, v0, v19
	v_sub_f32_e32 v0, v22, v41
	v_cvt_pk_bf16_f32 v19, v20, v21
	v_mul_f32_e32 v0, 0x3fb8aa3b, v0
	v_sub_f32_e32 v21, v23, v41
	v_exp_f32_e32 v0, v0
	v_mul_f32_e32 v21, 0x3fb8aa3b, v21
	v_sub_f32_e32 v22, v24, v41
	v_exp_f32_e32 v21, v21
	v_mul_f32_e32 v22, 0x3fb8aa3b, v22
	v_sub_f32_e32 v23, v25, v41
	v_exp_f32_e32 v22, v22
	v_mul_f32_e32 v23, 0x3fb8aa3b, v23
	v_exp_f32_e32 v23, v23
	v_add_f32_e32 v20, v0, v26
	v_add_f32_e32 v20, v21, v20
	v_add_f32_e32 v20, v22, v20
	v_add_f32_e32 v24, v23, v20
	v_cvt_pk_bf16_f32 v20, v0, v21
	v_cvt_pk_bf16_f32 v21, v22, v23
	v_sub_f32_e32 v0, v159, v41
	ds_write2_b64 v38, v[18:19], v[20:21] offset0:24 offset1:28
	v_mul_f32_e32 v0, 0x3fb8aa3b, v0
	v_sub_f32_e32 v19, v160, v41
	v_exp_f32_e32 v0, v0
	v_mul_f32_e32 v19, 0x3fb8aa3b, v19
	v_sub_f32_e32 v20, v161, v41
	v_exp_f32_e32 v19, v19
	v_mul_f32_e32 v20, 0x3fb8aa3b, v20
	v_sub_f32_e32 v21, v162, v41
	v_exp_f32_e32 v20, v20
	v_mul_f32_e32 v21, 0x3fb8aa3b, v21
	v_exp_f32_e32 v21, v21
	v_add_f32_e32 v18, v0, v24
	v_add_f32_e32 v18, v19, v18
	v_add_f32_e32 v18, v20, v18
	v_add_f32_e32 v22, v21, v18
	v_cvt_pk_bf16_f32 v18, v0, v19
	v_cvt_pk_bf16_f32 v19, v20, v21
	v_mov_b32_e32 v0, v1
	ds_write2_b64 v38, v[18:19], v[0:1] offset0:32 offset1:36
	ds_bpermute_b32 v18, v107, v22
	v_mul_u32_u24_e32 v40, 0x230, v106
	v_add_u32_e32 v39, v38, v96
	v_add3_u32 v51, s46, v99, v40
	ds_read_b128 v[26:29], v51 offset:45824
	ds_read_b128 v[30:33], v51 offset:54784
	s_waitcnt lgkmcnt(2)
	v_add_f32_e32 v147, v22, v18
	ds_read_b128 v[18:21], v39
	ds_read_b128 v[22:25], v51 offset:36864
	ds_read_b128 v[34:37], v51 offset:63744
	s_waitcnt lgkmcnt(1)
	v_mfma_f32_16x16x32_bf16 v[22:25], v[22:25], v[18:21], 0
	ds_bpermute_b32 v148, v108, v147
	v_mfma_f32_16x16x32_bf16 v[26:29], v[26:29], v[18:21], 0
	v_mfma_f32_16x16x32_bf16 v[30:33], v[30:33], v[18:21], 0
	s_waitcnt lgkmcnt(1)
	v_mfma_f32_16x16x32_bf16 v[18:21], v[34:37], v[18:21], 0
	ds_read_b128 v[34:37], v39 offset:64
	ds_read_b128 v[150:153], v51 offset:36928
	s_waitcnt lgkmcnt(0)
	v_mfma_f32_16x16x32_bf16 v[22:25], v[150:153], v[34:37], v[22:25]
	ds_read_b128 v[150:153], v51 offset:45888
	s_waitcnt lgkmcnt(0)
	v_mfma_f32_16x16x32_bf16 v[26:29], v[150:153], v[34:37], v[26:29]
	ds_read_b128 v[150:153], v51 offset:54848
	s_waitcnt lgkmcnt(0)
	v_mfma_f32_16x16x32_bf16 v[30:33], v[150:153], v[34:37], v[30:33]
	ds_read_b128 v[150:153], v51 offset:63808
	s_waitcnt lgkmcnt(0)
	v_mfma_f32_16x16x32_bf16 v[18:21], v[150:153], v[34:37], v[18:21]
	ds_read_b128 v[34:37], v39 offset:128
	ds_read_b128 v[150:153], v51 offset:36992
	s_waitcnt lgkmcnt(0)
	v_mfma_f32_16x16x32_bf16 v[22:25], v[150:153], v[34:37], v[22:25]
	ds_read_b128 v[150:153], v51 offset:45952
	s_waitcnt lgkmcnt(0)
	v_mfma_f32_16x16x32_bf16 v[26:29], v[150:153], v[34:37], v[26:29]
	ds_read_b128 v[150:153], v51 offset:54912
	s_waitcnt lgkmcnt(0)
	v_mfma_f32_16x16x32_bf16 v[30:33], v[150:153], v[34:37], v[30:33]
	ds_read_b128 v[150:153], v51 offset:63872
	s_waitcnt lgkmcnt(0)
	v_mfma_f32_16x16x32_bf16 v[18:21], v[150:153], v[34:37], v[18:21]
	ds_read_b128 v[34:37], v39 offset:192
	ds_read_b128 v[150:153], v51 offset:37056
	s_waitcnt lgkmcnt(0)
	v_mfma_f32_16x16x32_bf16 v[22:25], v[150:153], v[34:37], v[22:25]
	ds_read_b128 v[150:153], v51 offset:46016
	s_waitcnt lgkmcnt(0)
	v_mfma_f32_16x16x32_bf16 v[150:153], v[150:153], v[34:37], v[26:29]
	s_nop 2
	ds_read_b128 v[26:29], v51 offset:54976
	s_waitcnt lgkmcnt(0)
	v_mfma_f32_16x16x32_bf16 v[26:29], v[26:29], v[34:37], v[30:33]
	s_nop 2
	ds_read_b128 v[30:33], v51 offset:63936
	s_waitcnt lgkmcnt(0)
	v_mfma_f32_16x16x32_bf16 v[18:21], v[30:33], v[34:37], v[18:21]
	ds_read_b128 v[34:37], v39 offset:256
	ds_read_b128 v[30:33], v51 offset:37120
	s_waitcnt lgkmcnt(0)
	v_mfma_f32_16x16x32_bf16 v[22:25], v[30:33], v[34:37], v[22:25]
	ds_read_b128 v[30:33], v51 offset:46080
	s_waitcnt lgkmcnt(0)
	v_mfma_f32_16x16x32_bf16 v[30:33], v[30:33], v[34:37], v[150:153]
	s_nop 2
	ds_read_b128 v[150:153], v51 offset:55040
	s_waitcnt lgkmcnt(0)
	v_mfma_f32_16x16x32_bf16 v[26:29], v[150:153], v[34:37], v[26:29]
	ds_read_b128 v[150:153], v51 offset:64000
	v_ashrrev_i32_e32 v51, 31, v50
	s_waitcnt lgkmcnt(0)
	v_mfma_f32_16x16x32_bf16 v[18:21], v[150:153], v[34:37], v[18:21]
	v_cndmask_b32_e64 v34, 0, 1, s[76:77]
	v_cmp_ne_u32_e64 s[46:47], 1, v34
	s_cbranch_vccnz .LBB0_268
	v_sub_f32_e32 v37, v97, v41
	s_or_b32 s94, s78, s88
	v_mul_f32_e32 v37, 0x3fb8aa3b, v37
	v_or_b32_e32 v36, s94, v106
	v_readlane_b32 s94, v254, 32
	v_exp_f32_e32 v37, v37
	v_readlane_b32 s95, v254, 33
	s_nop 1
	v_mov_b64_e32 v[34:35], s[94:95]
	s_movk_i32 s94, 0x1c00
	v_mad_u64_u32 v[34:35], s[94:95], v36, s94, v[34:35]
	v_add_f32_e32 v36, v147, v148
	v_add_f32_e32 v36, v37, v36
	v_div_scale_f32 v37, s[94:95], v36, v36, 1.0
	v_rcp_f32_e32 v41, v37
	v_mad_i32_i24 v35, s79, v210, v35
	v_lshl_add_u64 v[34:35], s[2:3], 1, v[34:35]
	v_lshl_add_u64 v[34:35], v[50:51], 1, v[34:35]
	v_fma_f32 v96, -v37, v41, 1.0
	v_fmac_f32_e32 v41, v96, v41
	v_div_scale_f32 v96, vcc, 1.0, v36, 1.0
	v_mul_f32_e32 v147, v96, v41
	v_fma_f32 v148, -v37, v147, v96
	v_fmac_f32_e32 v147, v148, v41
	v_fma_f32 v37, -v37, v147, v96
	v_div_fmas_f32 v37, v37, v41, v147
	v_div_fixup_f32 v36, v37, v36, 1.0
	v_pk_mul_f32 v[24:25], v[24:25], v[36:37] op_sel_hi:[1,0]
	v_pk_mul_f32 v[22:23], v[22:23], v[36:37] op_sel_hi:[1,0]
	v_pk_mul_f32 v[32:33], v[32:33], v[36:37] op_sel_hi:[1,0]
	v_pk_mul_f32 v[30:31], v[30:31], v[36:37] op_sel_hi:[1,0]
	v_cvt_pk_bf16_f32 v22, v22, v23
	v_cvt_pk_bf16_f32 v23, v24, v25
	v_pk_mul_f32 v[20:21], v[36:37], v[20:21] op_sel_hi:[0,1]
	v_pk_mul_f32 v[18:19], v[36:37], v[18:19] op_sel_hi:[0,1]
	v_pk_mul_f32 v[28:29], v[36:37], v[28:29] op_sel_hi:[0,1]
	v_pk_mul_f32 v[26:27], v[36:37], v[26:27] op_sel_hi:[0,1]
	global_store_dwordx2 v[34:35], v[22:23], off offset:2048
	v_cvt_pk_bf16_f32 v22, v30, v31
	v_cvt_pk_bf16_f32 v23, v32, v33
	s_movk_i32 s95, 0x1c00
	s_movk_i32 s94, 0x80
	global_store_dwordx2 v[34:35], v[22:23], off offset:2080
	v_cvt_pk_bf16_f32 v22, v26, v27
	v_cvt_pk_bf16_f32 v23, v28, v29
	v_cvt_pk_bf16_f32 v18, v18, v19
	v_cvt_pk_bf16_f32 v19, v20, v21
	global_store_dwordx2 v[34:35], v[22:23], off offset:2112
	global_store_dwordx2 v[34:35], v[18:19], off offset:2144
